# PLE gate epilogue: last row group of each batch loaded under the processing of the first three (its ssq partial load issued first, per-load vmcnt waits)
# speedup vs baseline: 1.0044x; 1.0044x over previous
.LBB0_948:
	s_lshl_b32 s10, s20, 8
	s_add_i32 s10, s10, s61
	v_mbcnt_lo_u32_b32 v124, -1, 0
	v_mbcnt_hi_u32_b32 v124, -1, v124
	s_nop 0
	v_ashrrev_i32_e32 v122, 1, v124
	v_and_or_b32 v208, v124, 15, s10
	s_lshl_b32 s10, s82, 8
	v_and_b32_e32 v122, -8, v122
	s_or_b32 s10, s10, s68
	v_add_u32_e32 v204, s10, v122
	v_ashrrev_i32_e32 v122, 2, v124
	v_and_b32_e32 v122, -4, v122
	v_ashrrev_i32_e32 v123, 31, v122
	v_ashrrev_i32_e32 v209, 31, v208
	v_ashrrev_i32_e32 v205, 31, v204
	v_lshl_add_u64 v[206:207], v[122:123], 2, s[6:7]
	v_lshlrev_b64 v[122:123], 10, v[208:209]
	v_lshl_add_u64 v[122:123], v[122:123], 0, v[204:205]
	v_lshlrev_b32_e32 v125, 2, v124
	v_lshlrev_b64 v[122:123], 1, v[122:123]
	v_xor_b32_e32 v229, 64, v125
	v_xor_b32_e32 v228, 0x80, v125
	v_cmp_gt_u32_e32 vcc, 16, v124
	v_lshl_add_u64 v[124:125], s[88:89], 0, v[122:123]
	v_lshl_add_u64 v[122:123], s[62:63], 0, v[122:123]
	v_lshlrev_b64 v[226:227], 6, v[208:209]
	global_load_dwordx4 v[190:193], v[124:125], off
	global_load_dwordx4 v[186:189], v[122:123], off
	global_load_dwordx4 v[182:185], v[124:125], off offset:256
	global_load_dwordx4 v[178:181], v[122:123], off offset:256
	v_lshl_add_u64 v[122:123], v[206:207], 0, v[226:227]
	global_load_dwordx4 v[122:125], v[122:123], off
	v_or_b32_e32 v224, 16, v208
	v_ashrrev_i32_e32 v225, 31, v224
	v_lshlrev_b64 v[222:223], 6, v[224:225]
	v_or_b32_e32 v218, 32, v208
	v_ashrrev_i32_e32 v219, 31, v218
	v_lshlrev_b64 v[220:221], 6, v[218:219]
	v_or_b32_e32 v214, 48, v208
	v_ashrrev_i32_e32 v215, 31, v214
	v_lshlrev_b64 v[216:217], 6, v[214:215]
	v_lshl_add_u64 v[210:211], v[206:207], 0, v[216:217]
	s_waitcnt vmcnt(0)
	v_lshlrev_b32_e32 v238, 16, v190
	v_and_b32_e32 v239, 0xffff0000, v190
	v_lshlrev_b32_e32 v190, 16, v191
	v_and_b32_e32 v191, 0xffff0000, v191
	v_mov_b32_e32 v126, v123
	v_mov_b32_e32 v127, v124
	v_mov_b32_e32 v123, v125
	v_pk_add_f32 v[122:123], v[126:127], v[122:123]
	s_nop 0
	v_add_f32_e32 v122, v122, v123
	ds_bpermute_b32 v123, v229, v122
	s_waitcnt lgkmcnt(0)
	v_add_f32_e32 v122, v122, v123
	ds_bpermute_b32 v123, v228, v122
	s_waitcnt lgkmcnt(0)
	v_add_f32_e32 v122, v122, v123
	v_fmamk_f32 v122, v122, 0x3a800000, v240
	v_rsq_f32_e32 v236, v122
	v_lshlrev_b64 v[122:123], 10, v[224:225]
	v_lshl_add_u64 v[122:123], v[122:123], 0, v[204:205]
	v_lshlrev_b64 v[122:123], 1, v[122:123]
	v_lshl_add_u64 v[124:125], s[88:89], 0, v[122:123]
	v_lshl_add_u64 v[122:123], s[62:63], 0, v[122:123]
	global_load_dwordx4 v[174:177], v[124:125], off
	global_load_dwordx4 v[170:173], v[122:123], off
	global_load_dwordx4 v[166:169], v[124:125], off offset:256
	global_load_dwordx4 v[162:165], v[122:123], off offset:256
	v_lshl_add_u64 v[122:123], v[206:207], 0, v[222:223]
	global_load_dwordx4 v[122:125], v[122:123], off
	v_mul_f32_e32 v152, v152, v236
	v_mul_f32_e32 v153, v153, v236
	v_mul_f32_e32 v152, 0xbfb8aa3b, v152
	v_mul_f32_e32 v153, 0xbfb8aa3b, v153
	v_mul_f32_e32 v130, v130, v236
	v_mul_f32_e32 v131, v131, v236
	v_exp_f32_e32 v152, v152
	v_exp_f32_e32 v153, v153
	v_mul_f32_e32 v130, 0xbfb8aa3b, v130
	v_mul_f32_e32 v131, 0xbfb8aa3b, v131
	v_exp_f32_e32 v130, v130
	v_exp_f32_e32 v131, v131
	v_add_f32_e32 v152, 1.0, v152
	v_add_f32_e32 v153, 1.0, v153
	v_rcp_f32_e32 v152, v152
	v_rcp_f32_e32 v153, v153
	v_add_f32_e32 v130, 1.0, v130
	v_add_f32_e32 v131, 1.0, v131
	v_rcp_f32_e32 v130, v130
	v_rcp_f32_e32 v131, v131
	v_mul_f32_e32 v150, v150, v236
	v_mul_f32_e32 v151, v151, v236
	v_mul_f32_e32 v150, 0xbfb8aa3b, v150
	v_mul_f32_e32 v151, 0xbfb8aa3b, v151
	v_exp_f32_e32 v150, v150
	v_exp_f32_e32 v151, v151
	v_mul_f32_e32 v118, v118, v236
	v_mul_f32_e32 v119, v119, v236
	v_add_f32_e32 v150, 1.0, v150
	v_add_f32_e32 v151, 1.0, v151
	v_rcp_f32_e32 v150, v150
	v_rcp_f32_e32 v151, v151
	v_mul_f32_e32 v118, 0xbfb8aa3b, v118
	v_mul_f32_e32 v119, 0xbfb8aa3b, v119
	v_mul_f32_e32 v120, v120, v236
	v_mul_f32_e32 v121, v121, v236
	v_exp_f32_e32 v118, v118
	v_exp_f32_e32 v119, v119
	v_mul_f32_e32 v120, 0xbfb8aa3b, v120
	v_mul_f32_e32 v121, 0xbfb8aa3b, v121
	v_mul_f32_e32 v114, v114, v236
	v_mul_f32_e32 v115, v115, v236
	v_exp_f32_e32 v120, v120
	v_exp_f32_e32 v121, v121
	v_mul_f32_e32 v114, 0xbfb8aa3b, v114
	v_mul_f32_e32 v115, 0xbfb8aa3b, v115
	v_exp_f32_e32 v114, v114
	v_exp_f32_e32 v115, v115
	v_add_f32_e32 v118, 1.0, v118
	v_add_f32_e32 v119, 1.0, v119
	v_rcp_f32_e32 v118, v118
	v_rcp_f32_e32 v119, v119
	v_add_f32_e32 v120, 1.0, v120
	v_add_f32_e32 v121, 1.0, v121
	v_rcp_f32_e32 v120, v120
	v_rcp_f32_e32 v121, v121
	v_add_f32_e32 v114, 1.0, v114
	v_add_f32_e32 v115, 1.0, v115
	v_rcp_f32_e32 v114, v114
	v_rcp_f32_e32 v115, v115
	s_waitcnt vmcnt(0)
	v_add_f32_e32 v122, v122, v123
	v_add_f32_e32 v123, v124, v125
	v_add_f32_e32 v122, v122, v123
	ds_bpermute_b32 v123, v229, v122
	s_waitcnt lgkmcnt(0)
	v_add_f32_e32 v234, v122, v123
	v_lshlrev_b64 v[122:123], 10, v[218:219]
	v_lshl_add_u64 v[122:123], v[122:123], 0, v[204:205]
	v_lshlrev_b64 v[122:123], 1, v[122:123]
	v_lshl_add_u64 v[124:125], s[88:89], 0, v[122:123]
	v_lshl_add_u64 v[122:123], s[62:63], 0, v[122:123]
	global_load_dwordx4 v[158:161], v[124:125], off
	global_load_dwordx4 v[154:157], v[122:123], off
	global_load_dwordx4 v[146:149], v[124:125], off offset:256
	global_load_dwordx4 v[142:145], v[122:123], off offset:256
	v_lshl_add_u64 v[122:123], v[206:207], 0, v[220:221]
	global_load_dwordx4 v[122:125], v[122:123], off
	ds_bpermute_b32 v235, v228, v234
	s_waitcnt vmcnt(0)
	global_load_dwordx4 v[242:245], v[210:211], off
	v_add_f32_e32 v122, v122, v123
	v_add_f32_e32 v123, v124, v125
	v_add_f32_e32 v122, v122, v123
	ds_bpermute_b32 v123, v229, v122
	s_waitcnt lgkmcnt(0)
	v_add_f32_e32 v232, v122, v123
	v_lshlrev_b64 v[122:123], 10, v[214:215]
	v_lshl_add_u64 v[122:123], v[122:123], 0, v[204:205]
	v_lshlrev_b64 v[122:123], 1, v[122:123]
	v_lshl_add_u64 v[124:125], s[88:89], 0, v[122:123]
	v_lshl_add_u64 v[122:123], s[62:63], 0, v[122:123]
	global_load_dwordx4 v[138:141], v[124:125], off
	global_load_dwordx4 v[134:137], v[122:123], off
	global_load_dwordx4 v[126:129], v[124:125], off offset:256
	s_nop 0
	global_load_dwordx4 v[122:125], v[122:123], off offset:256
	ds_bpermute_b32 v233, v228, v232
	s_waitcnt vmcnt(4)
	v_add_f32_e32 v210, v242, v243
	v_lshlrev_b32_e32 v242, 16, v186
	v_and_b32_e32 v243, 0xffff0000, v186
	v_lshlrev_b32_e32 v186, 16, v187
	v_and_b32_e32 v187, 0xffff0000, v187
	v_pk_fma_f32 v[152:153], v[152:153], v[186:187], v[190:191]
	v_lshlrev_b32_e32 v186, 16, v192
	v_and_b32_e32 v187, 0xffff0000, v192
	v_lshlrev_b32_e32 v190, 16, v188
	v_and_b32_e32 v191, 0xffff0000, v188
	v_pk_fma_f32 v[186:187], v[130:131], v[190:191], v[186:187]
	v_mul_f32_e32 v130, v132, v236
	v_mul_f32_e32 v131, v133, v236
	v_mul_f32_e32 v130, 0xbfb8aa3b, v130
	v_mul_f32_e32 v131, 0xbfb8aa3b, v131
	v_exp_f32_e32 v130, v130
	v_exp_f32_e32 v131, v131
	v_add_f32_e32 v211, v244, v245
	v_add_f32_e32 v210, v210, v211
	ds_bpermute_b32 v211, v229, v210
	v_add_f32_e32 v130, 1.0, v130
	v_add_f32_e32 v131, 1.0, v131
	v_rcp_f32_e32 v130, v130
	v_rcp_f32_e32 v131, v131
	s_waitcnt lgkmcnt(0)
	v_add_f32_e32 v230, v210, v211
	v_lshlrev_b64 v[210:211], 11, v[208:209]
	v_pk_fma_f32 v[150:151], v[150:151], v[242:243], v[238:239]
	v_lshlrev_b32_e32 v132, 16, v193
	v_and_b32_e32 v133, 0xffff0000, v193
	v_lshlrev_b32_e32 v188, 16, v189
	v_and_b32_e32 v189, 0xffff0000, v189
	v_pk_fma_f32 v[188:189], v[130:131], v[188:189], v[132:133]
	v_cvt_pk_bf16_f32 v130, v150, v151
	v_lshl_add_u64 v[150:151], s[92:93], 0, v[210:211]
	v_cvt_pk_bf16_f32 v131, v152, v153
	v_cvt_pk_bf16_f32 v132, v186, v187
	v_cvt_pk_bf16_f32 v133, v188, v189
	v_lshl_add_u64 v[150:151], v[204:205], 1, v[150:151]
	global_store_dwordx4 v[150:151], v[130:133], off
	v_lshlrev_b32_e32 v152, 16, v130
	v_lshlrev_b32_e32 v153, 16, v131
	v_and_b32_e32 v130, 0xffff0000, v130
	v_and_b32_e32 v131, 0xffff0000, v131
	v_mul_f32_e32 v130, v130, v130
	v_mul_f32_e32 v131, v131, v131
	v_lshlrev_b32_e32 v186, 16, v132
	v_and_b32_e32 v132, 0xffff0000, v132
	v_fmac_f32_e32 v130, v152, v152
	v_fmac_f32_e32 v131, v153, v153
	v_add_f32_e32 v130, v130, v131
	v_mul_f32_e32 v131, v132, v132
	v_lshlrev_b32_e32 v187, 16, v133
	v_and_b32_e32 v133, 0xffff0000, v133
	v_fmac_f32_e32 v131, v186, v186
	v_add_f32_e32 v130, v131, v130
	v_mul_f32_e32 v131, v133, v133
	v_fmac_f32_e32 v131, v187, v187
	v_add_f32_e32 v152, v131, v130
	v_lshlrev_b32_e32 v130, 16, v182
	v_and_b32_e32 v131, 0xffff0000, v182
	v_lshlrev_b32_e32 v132, 16, v178
	v_and_b32_e32 v133, 0xffff0000, v178
	v_pk_fma_f32 v[118:119], v[118:119], v[132:133], v[130:131]
	v_lshlrev_b32_e32 v130, 16, v183
	v_and_b32_e32 v131, 0xffff0000, v183
	v_lshlrev_b32_e32 v132, 16, v179
	v_and_b32_e32 v133, 0xffff0000, v179
	v_pk_fma_f32 v[120:121], v[120:121], v[132:133], v[130:131]
	v_lshlrev_b32_e32 v130, 16, v184
	v_and_b32_e32 v131, 0xffff0000, v184
	v_lshlrev_b32_e32 v132, 16, v180
	v_and_b32_e32 v133, 0xffff0000, v180
	v_pk_fma_f32 v[130:131], v[114:115], v[132:133], v[130:131]
	v_mul_f32_e32 v114, v116, v236
	v_mul_f32_e32 v115, v117, v236
	v_mul_f32_e32 v114, 0xbfb8aa3b, v114
	v_mul_f32_e32 v115, 0xbfb8aa3b, v115
	v_exp_f32_e32 v114, v114
	v_exp_f32_e32 v115, v115
	v_lshlrev_b32_e32 v116, 16, v185
	v_and_b32_e32 v117, 0xffff0000, v185
	v_add_f32_e32 v114, 1.0, v114
	v_add_f32_e32 v115, 1.0, v115
	v_rcp_f32_e32 v114, v114
	v_rcp_f32_e32 v115, v115
	v_lshlrev_b32_e32 v132, 16, v181
	v_and_b32_e32 v133, 0xffff0000, v181
	ds_bpermute_b32 v231, v228, v230
	v_pk_fma_f32 v[132:133], v[114:115], v[132:133], v[116:117]
	v_cvt_pk_bf16_f32 v114, v118, v119
	v_cvt_pk_bf16_f32 v115, v120, v121
	v_cvt_pk_bf16_f32 v116, v130, v131
	v_cvt_pk_bf16_f32 v117, v132, v133
	global_store_dwordx4 v[150:151], v[114:117], off offset:256
	v_lshlrev_b32_e32 v118, 16, v114
	v_lshlrev_b32_e32 v119, 16, v115
	v_and_b32_e32 v114, 0xffff0000, v114
	v_and_b32_e32 v115, 0xffff0000, v115
	v_mul_f32_e32 v114, v114, v114
	v_fmac_f32_e32 v114, v118, v118
	v_mul_f32_e32 v115, v115, v115
	v_lshlrev_b32_e32 v120, 16, v116
	v_and_b32_e32 v116, 0xffff0000, v116
	v_add_f32_e32 v114, v114, v152
	v_fmac_f32_e32 v115, v119, v119
	v_add_f32_e32 v114, v115, v114
	v_mul_f32_e32 v115, v116, v116
	v_lshlrev_b32_e32 v121, 16, v117
	v_and_b32_e32 v117, 0xffff0000, v117
	v_fmac_f32_e32 v115, v120, v120
	v_add_f32_e32 v114, v115, v114
	v_mul_f32_e32 v115, v117, v117
	v_fmac_f32_e32 v115, v121, v121
	v_add_f32_e32 v114, v115, v114
	ds_bpermute_b32 v115, v229, v114
	s_waitcnt lgkmcnt(0)
	v_add_f32_e32 v114, v114, v115
	ds_bpermute_b32 v115, v228, v114
	s_and_saveexec_b64 s[10:11], vcc
	s_cbranch_execz .LBB0_950
	s_lshl_b32 s20, s82, 2
	v_lshl_add_u64 v[116:117], s[4:5], 0, v[226:227]
	s_ashr_i32 s21, s20, 31
	v_lshl_add_u64 v[116:117], s[20:21], 2, v[116:117]
	s_lshl_b32 s76, s19, 2
	v_lshl_add_u64 v[116:117], v[116:117], 0, s[76:77]
	s_waitcnt lgkmcnt(0)
	v_add_f32_e32 v114, v114, v115
	global_store_dword v[116:117], v114, off

.LBB0_956:
	s_or_b64 exec, exec, s[10:11]
	v_add_u32_e32 v144, 0x80, v208
	v_ashrrev_i32_e32 v145, 31, v144
	s_waitcnt lgkmcnt(0)
	v_lshlrev_b64 v[66:67], 10, v[144:145]
	v_lshl_add_u64 v[66:67], v[66:67], 0, v[204:205]
	v_lshlrev_b64 v[66:67], 1, v[66:67]
	v_lshl_add_u64 v[68:69], s[88:89], 0, v[66:67]
	v_lshl_add_u64 v[66:67], s[62:63], 0, v[66:67]
	v_lshlrev_b64 v[142:143], 6, v[144:145]
	global_load_dwordx4 v[126:129], v[68:69], off
	global_load_dwordx4 v[122:125], v[66:67], off
	global_load_dwordx4 v[118:121], v[68:69], off offset:256
	global_load_dwordx4 v[114:117], v[66:67], off offset:256
	v_lshl_add_u64 v[66:67], v[206:207], 0, v[142:143]
	global_load_dwordx4 v[66:69], v[66:67], off
	v_add_u32_e32 v140, 0x90, v208
	v_ashrrev_i32_e32 v141, 31, v140
	v_lshlrev_b64 v[138:139], 6, v[140:141]
	v_add_u32_e32 v134, 0xa0, v208
	v_ashrrev_i32_e32 v135, 31, v134
	v_lshlrev_b64 v[136:137], 6, v[134:135]
	v_add_u32_e32 v130, 0xb0, v208
	v_ashrrev_i32_e32 v131, 31, v130
	v_lshlrev_b64 v[132:133], 6, v[130:131]
	v_lshl_add_u64 v[146:147], v[206:207], 0, v[132:133]
	v_lshlrev_b64 v[144:145], 11, v[144:145]
	s_waitcnt vmcnt(0)
	v_mov_b32_e32 v70, v67
	v_mov_b32_e32 v71, v68
	v_mov_b32_e32 v67, v69
	v_pk_add_f32 v[66:67], v[70:71], v[66:67]
	s_nop 0
	v_add_f32_e32 v66, v66, v67
	ds_bpermute_b32 v67, v229, v66
	s_waitcnt lgkmcnt(0)
	v_add_f32_e32 v66, v66, v67
	ds_bpermute_b32 v67, v228, v66
	s_waitcnt lgkmcnt(0)
	v_add_f32_e32 v66, v66, v67
	v_fmamk_f32 v66, v66, 0x3a800000, v240
	v_rsq_f32_e32 v152, v66
	v_lshlrev_b64 v[66:67], 10, v[140:141]
	v_lshl_add_u64 v[66:67], v[66:67], 0, v[204:205]
	v_lshlrev_b64 v[66:67], 1, v[66:67]
	v_lshl_add_u64 v[68:69], s[88:89], 0, v[66:67]
	v_lshl_add_u64 v[66:67], s[62:63], 0, v[66:67]
	global_load_dwordx4 v[110:113], v[68:69], off
	global_load_dwordx4 v[106:109], v[66:67], off
	global_load_dwordx4 v[102:105], v[68:69], off offset:256
	global_load_dwordx4 v[98:101], v[66:67], off offset:256
	v_lshl_add_u64 v[66:67], v[206:207], 0, v[138:139]
	global_load_dwordx4 v[66:69], v[66:67], off
	v_mul_f32_e32 v64, v64, v152
	v_mul_f32_e32 v65, v65, v152
	v_mul_f32_e32 v64, 0xbfb8aa3b, v64
	v_mul_f32_e32 v65, 0xbfb8aa3b, v65
	v_mul_f32_e32 v58, v58, v152
	v_mul_f32_e32 v59, v59, v152
	v_exp_f32_e32 v64, v64
	v_exp_f32_e32 v65, v65
	v_mul_f32_e32 v58, 0xbfb8aa3b, v58
	v_mul_f32_e32 v59, 0xbfb8aa3b, v59
	v_exp_f32_e32 v58, v58
	v_exp_f32_e32 v59, v59
	v_add_f32_e32 v64, 1.0, v64
	v_add_f32_e32 v65, 1.0, v65
	v_rcp_f32_e32 v64, v64
	v_rcp_f32_e32 v65, v65
	v_add_f32_e32 v58, 1.0, v58
	v_add_f32_e32 v59, 1.0, v59
	v_rcp_f32_e32 v58, v58
	v_rcp_f32_e32 v59, v59
	v_mul_f32_e32 v62, v62, v152
	v_mul_f32_e32 v63, v63, v152
	v_mul_f32_e32 v62, 0xbfb8aa3b, v62
	v_mul_f32_e32 v63, 0xbfb8aa3b, v63
	v_exp_f32_e32 v62, v62
	v_exp_f32_e32 v63, v63
	v_mul_f32_e32 v54, v54, v152
	v_mul_f32_e32 v55, v55, v152
	v_add_f32_e32 v62, 1.0, v62
	v_add_f32_e32 v63, 1.0, v63
	v_rcp_f32_e32 v62, v62
	v_rcp_f32_e32 v63, v63
	v_mul_f32_e32 v54, 0xbfb8aa3b, v54
	v_mul_f32_e32 v55, 0xbfb8aa3b, v55
	v_mul_f32_e32 v56, v56, v152
	v_mul_f32_e32 v57, v57, v152
	v_exp_f32_e32 v54, v54
	v_exp_f32_e32 v55, v55
	v_mul_f32_e32 v56, 0xbfb8aa3b, v56
	v_mul_f32_e32 v57, 0xbfb8aa3b, v57
	v_mul_f32_e32 v50, v50, v152
	v_mul_f32_e32 v51, v51, v152
	v_exp_f32_e32 v56, v56
	v_exp_f32_e32 v57, v57
	v_mul_f32_e32 v50, 0xbfb8aa3b, v50
	v_mul_f32_e32 v51, 0xbfb8aa3b, v51
	v_exp_f32_e32 v50, v50
	v_exp_f32_e32 v51, v51
	v_add_f32_e32 v54, 1.0, v54
	v_add_f32_e32 v55, 1.0, v55
	v_rcp_f32_e32 v54, v54
	v_rcp_f32_e32 v55, v55
	v_add_f32_e32 v56, 1.0, v56
	v_add_f32_e32 v57, 1.0, v57
	v_rcp_f32_e32 v56, v56
	v_rcp_f32_e32 v57, v57
	v_add_f32_e32 v50, 1.0, v50
	v_add_f32_e32 v51, 1.0, v51
	v_rcp_f32_e32 v50, v50
	v_rcp_f32_e32 v51, v51
	s_waitcnt vmcnt(0)
	v_add_f32_e32 v66, v66, v67
	v_add_f32_e32 v67, v68, v69
	v_add_f32_e32 v66, v66, v67
	ds_bpermute_b32 v67, v229, v66
	s_waitcnt lgkmcnt(0)
	v_add_f32_e32 v150, v66, v67
	v_lshlrev_b64 v[66:67], 10, v[134:135]
	v_lshl_add_u64 v[66:67], v[66:67], 0, v[204:205]
	v_lshlrev_b64 v[66:67], 1, v[66:67]
	v_lshl_add_u64 v[68:69], s[88:89], 0, v[66:67]
	v_lshl_add_u64 v[66:67], s[62:63], 0, v[66:67]
	global_load_dwordx4 v[94:97], v[68:69], off
	global_load_dwordx4 v[90:93], v[66:67], off
	global_load_dwordx4 v[86:89], v[68:69], off offset:256
	global_load_dwordx4 v[82:85], v[66:67], off offset:256
	v_lshl_add_u64 v[66:67], v[206:207], 0, v[136:137]
	global_load_dwordx4 v[66:69], v[66:67], off
	ds_bpermute_b32 v151, v228, v150
	s_waitcnt vmcnt(0)
	global_load_dwordx4 v[154:157], v[146:147], off
	v_add_f32_e32 v66, v66, v67
	v_add_f32_e32 v67, v68, v69
	v_add_f32_e32 v66, v66, v67
	ds_bpermute_b32 v67, v229, v66
	s_waitcnt lgkmcnt(0)
	v_add_f32_e32 v148, v66, v67
	v_lshlrev_b64 v[66:67], 10, v[130:131]
	v_lshl_add_u64 v[66:67], v[66:67], 0, v[204:205]
	v_lshlrev_b64 v[66:67], 1, v[66:67]
	v_lshl_add_u64 v[68:69], s[88:89], 0, v[66:67]
	v_lshl_add_u64 v[66:67], s[62:63], 0, v[66:67]
	global_load_dwordx4 v[78:81], v[68:69], off
	global_load_dwordx4 v[74:77], v[66:67], off
	global_load_dwordx4 v[70:73], v[68:69], off offset:256
	s_nop 0
	global_load_dwordx4 v[66:69], v[66:67], off offset:256
	ds_bpermute_b32 v149, v228, v148
	s_waitcnt vmcnt(4)
	v_add_f32_e32 v146, v154, v155
	v_add_f32_e32 v147, v156, v157
	v_lshlrev_b32_e32 v154, 16, v126
	v_and_b32_e32 v155, 0xffff0000, v126
	v_lshlrev_b32_e32 v156, 16, v122
	v_and_b32_e32 v157, 0xffff0000, v122
	v_lshlrev_b32_e32 v126, 16, v127
	v_and_b32_e32 v127, 0xffff0000, v127
	v_lshlrev_b32_e32 v122, 16, v123
	v_and_b32_e32 v123, 0xffff0000, v123
	v_pk_fma_f32 v[64:65], v[64:65], v[122:123], v[126:127]
	v_lshlrev_b32_e32 v122, 16, v128
	v_and_b32_e32 v123, 0xffff0000, v128
	v_lshlrev_b32_e32 v126, 16, v124
	v_and_b32_e32 v127, 0xffff0000, v124
	v_pk_fma_f32 v[122:123], v[58:59], v[126:127], v[122:123]
	v_mul_f32_e32 v58, v60, v152
	v_mul_f32_e32 v59, v61, v152
	v_mul_f32_e32 v58, 0xbfb8aa3b, v58
	v_mul_f32_e32 v59, 0xbfb8aa3b, v59
	v_exp_f32_e32 v58, v58
	v_exp_f32_e32 v59, v59
	v_pk_fma_f32 v[62:63], v[62:63], v[156:157], v[154:155]
	v_lshlrev_b32_e32 v60, 16, v129
	v_add_f32_e32 v58, 1.0, v58
	v_add_f32_e32 v59, 1.0, v59
	v_rcp_f32_e32 v58, v58
	v_rcp_f32_e32 v59, v59
	v_and_b32_e32 v61, 0xffff0000, v129
	v_lshlrev_b32_e32 v124, 16, v125
	v_and_b32_e32 v125, 0xffff0000, v125
	v_pk_fma_f32 v[124:125], v[58:59], v[124:125], v[60:61]
	v_cvt_pk_bf16_f32 v58, v62, v63
	v_lshl_add_u64 v[62:63], s[92:93], 0, v[144:145]
	v_cvt_pk_bf16_f32 v59, v64, v65
	v_cvt_pk_bf16_f32 v60, v122, v123
	v_cvt_pk_bf16_f32 v61, v124, v125
	v_lshl_add_u64 v[62:63], v[204:205], 1, v[62:63]
	global_store_dwordx4 v[62:63], v[58:61], off
	v_lshlrev_b32_e32 v64, 16, v58
	v_lshlrev_b32_e32 v65, 16, v59
	v_and_b32_e32 v58, 0xffff0000, v58
	v_and_b32_e32 v59, 0xffff0000, v59
	v_mul_f32_e32 v58, v58, v58
	v_mul_f32_e32 v59, v59, v59
	v_lshlrev_b32_e32 v122, 16, v60
	v_and_b32_e32 v60, 0xffff0000, v60
	v_fmac_f32_e32 v58, v64, v64
	v_fmac_f32_e32 v59, v65, v65
	v_add_f32_e32 v58, v58, v59
	v_mul_f32_e32 v59, v60, v60
	v_lshlrev_b32_e32 v123, 16, v61
	v_and_b32_e32 v61, 0xffff0000, v61
	v_fmac_f32_e32 v59, v122, v122
	v_add_f32_e32 v58, v59, v58
	v_mul_f32_e32 v59, v61, v61
	v_fmac_f32_e32 v59, v123, v123
	v_add_f32_e32 v64, v59, v58
	v_lshlrev_b32_e32 v58, 16, v118
	v_and_b32_e32 v59, 0xffff0000, v118
	v_lshlrev_b32_e32 v60, 16, v114
	v_and_b32_e32 v61, 0xffff0000, v114
	v_pk_fma_f32 v[54:55], v[54:55], v[60:61], v[58:59]
	v_lshlrev_b32_e32 v58, 16, v119
	v_and_b32_e32 v59, 0xffff0000, v119
	v_lshlrev_b32_e32 v60, 16, v115
	v_and_b32_e32 v61, 0xffff0000, v115
	v_pk_fma_f32 v[56:57], v[56:57], v[60:61], v[58:59]
	v_lshlrev_b32_e32 v58, 16, v120
	v_and_b32_e32 v59, 0xffff0000, v120
	v_lshlrev_b32_e32 v60, 16, v116
	v_and_b32_e32 v61, 0xffff0000, v116
	v_pk_fma_f32 v[58:59], v[50:51], v[60:61], v[58:59]
	v_mul_f32_e32 v50, v52, v152
	v_mul_f32_e32 v51, v53, v152
	v_mul_f32_e32 v50, 0xbfb8aa3b, v50
	v_mul_f32_e32 v51, 0xbfb8aa3b, v51
	v_exp_f32_e32 v50, v50
	v_exp_f32_e32 v51, v51
	v_lshlrev_b32_e32 v52, 16, v121
	v_and_b32_e32 v53, 0xffff0000, v121
	v_add_f32_e32 v50, 1.0, v50
	v_add_f32_e32 v51, 1.0, v51
	v_rcp_f32_e32 v50, v50
	v_rcp_f32_e32 v51, v51
	v_lshlrev_b32_e32 v60, 16, v117
	v_and_b32_e32 v61, 0xffff0000, v117
	v_add_f32_e32 v146, v146, v147
	v_pk_fma_f32 v[60:61], v[50:51], v[60:61], v[52:53]
	v_cvt_pk_bf16_f32 v50, v54, v55
	v_cvt_pk_bf16_f32 v51, v56, v57
	v_cvt_pk_bf16_f32 v52, v58, v59
	v_cvt_pk_bf16_f32 v53, v60, v61
	global_store_dwordx4 v[62:63], v[50:53], off offset:256
	v_lshlrev_b32_e32 v54, 16, v50
	v_lshlrev_b32_e32 v55, 16, v51
	v_and_b32_e32 v50, 0xffff0000, v50
	v_and_b32_e32 v51, 0xffff0000, v51
	v_mul_f32_e32 v50, v50, v50
	v_fmac_f32_e32 v50, v54, v54
	v_mul_f32_e32 v51, v51, v51
	v_lshlrev_b32_e32 v56, 16, v52
	v_and_b32_e32 v52, 0xffff0000, v52
	v_add_f32_e32 v50, v50, v64
	v_fmac_f32_e32 v51, v55, v55
	v_add_f32_e32 v50, v51, v50
	v_mul_f32_e32 v51, v52, v52
	v_lshlrev_b32_e32 v57, 16, v53
	v_and_b32_e32 v53, 0xffff0000, v53
	v_fmac_f32_e32 v51, v56, v56
	v_add_f32_e32 v50, v51, v50
	v_mul_f32_e32 v51, v53, v53
	v_fmac_f32_e32 v51, v57, v57
	v_add_f32_e32 v50, v51, v50
	ds_bpermute_b32 v147, v229, v146
	ds_bpermute_b32 v51, v229, v50
	s_waitcnt lgkmcnt(1)
	v_add_f32_e32 v146, v146, v147
	s_waitcnt lgkmcnt(0)
	v_add_f32_e32 v50, v50, v51
	ds_bpermute_b32 v147, v228, v146
	ds_bpermute_b32 v51, v228, v50
	s_and_saveexec_b64 s[10:11], vcc
	s_cbranch_execz .LBB0_958
	s_lshl_b32 s20, s82, 2
	v_lshl_add_u64 v[52:53], s[4:5], 0, v[142:143]
	s_ashr_i32 s21, s20, 31
	v_lshl_add_u64 v[52:53], s[20:21], 2, v[52:53]
	s_lshl_b32 s76, s19, 2
	v_lshl_add_u64 v[52:53], v[52:53], 0, s[76:77]
	s_waitcnt lgkmcnt(0)
	v_add_f32_e32 v50, v50, v51
	global_store_dword v[52:53], v50, off
